# setprio strategy: per-segment flips removed in the 3 K-loops, one static s_setprio 1 for waves 4-7 per unit
# speedup vs baseline: 1.0083x; 1.0017x over previous
.LBB0_179:
	s_add_u32 s0, s0, 0x40080
	s_addc_u32 s1, s1, 0
	s_add_u32 s53, s4, 0x100
	v_mov_b32_e32 v0, 0
	s_addc_u32 s79, s5, 0
	s_mov_b32 vcc_lo, -2
	v_mov_b32_e32 v1, v0
	v_mov_b32_e32 v2, v0
	v_mov_b32_e32 v3, v0
	v_mov_b32_e32 v4, v0
	v_mov_b32_e32 v5, v0
	v_mov_b32_e32 v6, v0
	v_mov_b32_e32 v7, v0
	v_mov_b32_e32 v16, v0
	v_mov_b32_e32 v17, v0
	v_mov_b32_e32 v18, v0
	v_mov_b32_e32 v19, v0
	v_mov_b32_e32 v20, v0
	v_mov_b32_e32 v21, v0
	v_mov_b32_e32 v22, v0
	v_mov_b32_e32 v23, v0
	v_mov_b32_e32 v32, v0
	v_mov_b32_e32 v33, v0
	v_mov_b32_e32 v34, v0
	v_mov_b32_e32 v35, v0
	v_mov_b32_e32 v36, v0
	v_mov_b32_e32 v37, v0
	v_mov_b32_e32 v38, v0
	v_mov_b32_e32 v39, v0
	v_mov_b32_e32 v48, v0
	v_mov_b32_e32 v49, v0
	v_mov_b32_e32 v50, v0
	v_mov_b32_e32 v51, v0
	v_mov_b32_e32 v52, v0
	v_mov_b32_e32 v53, v0
	v_mov_b32_e32 v54, v0
	v_mov_b32_e32 v55, v0
	v_mov_b32_e32 v8, v0
	v_mov_b32_e32 v9, v0
	v_mov_b32_e32 v10, v0
	v_mov_b32_e32 v11, v0
	v_mov_b32_e32 v12, v0
	v_mov_b32_e32 v13, v0
	v_mov_b32_e32 v14, v0
	v_mov_b32_e32 v15, v0
	v_mov_b32_e32 v24, v0
	v_mov_b32_e32 v25, v0
	v_mov_b32_e32 v26, v0
	v_mov_b32_e32 v27, v0
	v_mov_b32_e32 v28, v0
	v_mov_b32_e32 v29, v0
	v_mov_b32_e32 v30, v0
	v_mov_b32_e32 v31, v0
	v_mov_b32_e32 v40, v0
	v_mov_b32_e32 v41, v0
	v_mov_b32_e32 v42, v0
	v_mov_b32_e32 v43, v0
	v_mov_b32_e32 v44, v0
	v_mov_b32_e32 v45, v0
	v_mov_b32_e32 v46, v0
	v_mov_b32_e32 v47, v0
	v_mov_b32_e32 v56, v0
	v_mov_b32_e32 v57, v0
	v_mov_b32_e32 v58, v0
	v_mov_b32_e32 v59, v0
	v_mov_b32_e32 v60, v0
	v_mov_b32_e32 v61, v0
	v_mov_b32_e32 v62, v0
	v_mov_b32_e32 v63, v0
	v_mov_b32_e32 v64, v0
	v_mov_b32_e32 v65, v0
	v_mov_b32_e32 v66, v0
	v_mov_b32_e32 v67, v0
	v_mov_b32_e32 v68, v0
	v_mov_b32_e32 v69, v0
	v_mov_b32_e32 v70, v0
	v_mov_b32_e32 v71, v0
	v_mov_b32_e32 v80, v0
	v_mov_b32_e32 v81, v0
	v_mov_b32_e32 v82, v0
	v_mov_b32_e32 v83, v0
	v_mov_b32_e32 v84, v0
	v_mov_b32_e32 v85, v0
	v_mov_b32_e32 v86, v0
	v_mov_b32_e32 v87, v0
	v_mov_b32_e32 v96, v0
	v_mov_b32_e32 v97, v0
	v_mov_b32_e32 v98, v0
	v_mov_b32_e32 v99, v0
	v_mov_b32_e32 v100, v0
	v_mov_b32_e32 v101, v0
	v_mov_b32_e32 v102, v0
	v_mov_b32_e32 v103, v0
	v_mov_b32_e32 v112, v0
	v_mov_b32_e32 v113, v0
	v_mov_b32_e32 v114, v0
	v_mov_b32_e32 v115, v0
	v_mov_b32_e32 v116, v0
	v_mov_b32_e32 v117, v0
	v_mov_b32_e32 v118, v0
	v_mov_b32_e32 v119, v0
	v_mov_b32_e32 v72, v0
	v_mov_b32_e32 v73, v0
	v_mov_b32_e32 v74, v0
	v_mov_b32_e32 v75, v0
	v_mov_b32_e32 v76, v0
	v_mov_b32_e32 v77, v0
	v_mov_b32_e32 v78, v0
	v_mov_b32_e32 v79, v0
	v_mov_b32_e32 v88, v0
	v_mov_b32_e32 v89, v0
	v_mov_b32_e32 v90, v0
	v_mov_b32_e32 v91, v0
	v_mov_b32_e32 v92, v0
	v_mov_b32_e32 v93, v0
	v_mov_b32_e32 v94, v0
	v_mov_b32_e32 v95, v0
	v_mov_b32_e32 v104, v0
	v_mov_b32_e32 v105, v0
	v_mov_b32_e32 v106, v0
	v_mov_b32_e32 v107, v0
	v_mov_b32_e32 v108, v0
	v_mov_b32_e32 v109, v0
	v_mov_b32_e32 v110, v0
	v_mov_b32_e32 v111, v0
	v_mov_b32_e32 v120, v0
	v_mov_b32_e32 v121, v0
	v_mov_b32_e32 v122, v0
	v_mov_b32_e32 v123, v0
	v_mov_b32_e32 v124, v0
	v_mov_b32_e32 v125, v0
	v_mov_b32_e32 v126, v0
	v_mov_b32_e32 v127, v0
	v_readfirstlane_b32 s32, v201
	s_nop 3
	s_cmp_lt_u32 s32, 0x100
	s_cbranch_scc1 .Lprio_skip0
	s_setprio 1
.Lprio_skip0:
.LBB0_180:
	ds_read_b128 v[152:155], v159
	ds_read_b128 v[162:165], v159 offset:1024
	ds_read_b128 v[166:169], v159 offset:2048
	ds_read_b128 v[170:173], v159 offset:3072
	ds_read_b128 v[174:177], v160
	ds_read_b128 v[178:181], v160 offset:1024
	ds_read_b128 v[182:185], v160 offset:2048
	ds_read_b128 v[186:189], v160 offset:3072
	s_add_u32 s4, s0, 0xfffc0080
	s_addc_u32 s5, s1, -1
	s_cmp_eq_u32 vcc_lo, 12
	s_cselect_b32 s83, s39, s5
	s_cselect_b32 s82, s38, s4
	s_cselect_b32 s5, s73, s79
	s_cselect_b32 s4, s72, s53
	v_lshl_add_u64 v[198:199], s[0:1], 0, v[144:145]
	s_add_i32 m0, s43, 0xc000
	ds_read_b128 v[190:193], v161
	ds_read_b128 v[194:197], v161 offset:1024
	ds_read_b128 v[202:205], v161 offset:2048
	ds_read_b128 v[206:209], v161 offset:3072
	ds_read_b128 v[210:213], v161 offset:4096
	ds_read_b128 v[214:217], v161 offset:5120
	ds_read_b128 v[218:221], v161 offset:6144
	ds_read_b128 v[222:225], v161 offset:7168
	global_load_lds_dwordx4 v[198:199], off
	v_lshl_add_u64 v[198:199], s[0:1], 0, v[146:147]
	s_add_i32 m0, s43, 0xe000
	s_nop 0
	global_load_lds_dwordx4 v[198:199], off
	s_waitcnt vmcnt(8)
	s_waitcnt lgkmcnt(0)
	s_barrier
	s_waitcnt lgkmcnt(0)
	v_mfma_f32_16x16x32_bf16 v[124:127], v[152:155], v[190:193], v[124:127]
	v_mfma_f32_16x16x32_bf16 v[120:123], v[166:169], v[190:193], v[120:123]
	v_mfma_f32_16x16x32_bf16 v[108:111], v[152:155], v[202:205], v[108:111]
	v_mfma_f32_16x16x32_bf16 v[104:107], v[166:169], v[202:205], v[104:107]
	v_mfma_f32_16x16x32_bf16 v[92:95], v[152:155], v[210:213], v[92:95]
	v_mfma_f32_16x16x32_bf16 v[88:91], v[166:169], v[210:213], v[88:91]
	v_mfma_f32_16x16x32_bf16 v[76:79], v[152:155], v[218:221], v[76:79]
	v_mfma_f32_16x16x32_bf16 v[72:75], v[166:169], v[218:221], v[72:75]
	v_mfma_f32_16x16x32_bf16 v[124:127], v[162:165], v[194:197], v[124:127]
	v_mfma_f32_16x16x32_bf16 v[120:123], v[170:173], v[194:197], v[120:123]
	v_mfma_f32_16x16x32_bf16 v[108:111], v[162:165], v[206:209], v[108:111]
	v_mfma_f32_16x16x32_bf16 v[104:107], v[170:173], v[206:209], v[104:107]
	v_mfma_f32_16x16x32_bf16 v[92:95], v[162:165], v[214:217], v[92:95]
	v_mfma_f32_16x16x32_bf16 v[88:91], v[170:173], v[214:217], v[88:91]
	v_mfma_f32_16x16x32_bf16 v[76:79], v[162:165], v[222:225], v[76:79]
	v_mfma_f32_16x16x32_bf16 v[72:75], v[170:173], v[222:225], v[72:75]
	v_mfma_f32_16x16x32_bf16 v[116:119], v[174:177], v[190:193], v[116:119]
	v_mfma_f32_16x16x32_bf16 v[112:115], v[182:185], v[190:193], v[112:115]
	v_mfma_f32_16x16x32_bf16 v[100:103], v[174:177], v[202:205], v[100:103]
	v_mfma_f32_16x16x32_bf16 v[96:99], v[182:185], v[202:205], v[96:99]
	v_mfma_f32_16x16x32_bf16 v[84:87], v[174:177], v[210:213], v[84:87]
	v_mfma_f32_16x16x32_bf16 v[80:83], v[182:185], v[210:213], v[80:83]
	v_mfma_f32_16x16x32_bf16 v[68:71], v[174:177], v[218:221], v[68:71]
	v_mfma_f32_16x16x32_bf16 v[64:67], v[182:185], v[218:221], v[64:67]
	v_mfma_f32_16x16x32_bf16 v[116:119], v[178:181], v[194:197], v[116:119]
	v_mfma_f32_16x16x32_bf16 v[112:115], v[186:189], v[194:197], v[112:115]
	v_mfma_f32_16x16x32_bf16 v[100:103], v[178:181], v[206:209], v[100:103]
	v_mfma_f32_16x16x32_bf16 v[96:99], v[186:189], v[206:209], v[96:99]
	v_mfma_f32_16x16x32_bf16 v[84:87], v[178:181], v[214:217], v[84:87]
	v_mfma_f32_16x16x32_bf16 v[80:83], v[186:189], v[214:217], v[80:83]
	v_mfma_f32_16x16x32_bf16 v[68:71], v[178:181], v[222:225], v[68:71]
	v_mfma_f32_16x16x32_bf16 v[64:67], v[186:189], v[222:225], v[64:67]
	s_barrier
	s_add_i32 s12, s9, s3
	v_lshl_add_u64 v[198:199], s[4:5], 0, v[132:133]
	s_mov_b32 m0, s12
	ds_read_b128 v[190:193], v161 offset:16384
	ds_read_b128 v[194:197], v161 offset:17408
	ds_read_b128 v[202:205], v161 offset:18432
	ds_read_b128 v[206:209], v161 offset:19456
	ds_read_b128 v[210:213], v161 offset:20480
	ds_read_b128 v[214:217], v161 offset:21504
	ds_read_b128 v[218:221], v161 offset:22528
	ds_read_b128 v[222:225], v161 offset:23552
	global_load_lds_dwordx4 v[198:199], off
	s_add_i32 m0, s12, 0x2000
	s_add_u32 s12, s4, 0x40000
	v_lshl_add_u64 v[226:227], s[4:5], 0, v[128:129]
	s_addc_u32 s13, s5, 0
	s_add_i32 vcc_hi, s10, s3
	global_load_lds_dwordx4 v[226:227], off
	v_lshl_add_u64 v[228:229], s[12:13], 0, v[132:133]
	s_mov_b32 m0, vcc_hi
	v_lshl_add_u64 v[230:231], s[82:83], 0, v[130:131]
	global_load_lds_dwordx4 v[228:229], off
	v_lshl_add_u64 v[228:229], s[12:13], 0, v[128:129]
	s_add_i32 m0, vcc_hi, 0x2000
	s_nop 0
	global_load_lds_dwordx4 v[228:229], off
	v_lshl_add_u64 v[228:229], s[82:83], 0, v[134:135]
	s_mov_b32 m0, s43
	s_nop 0
	global_load_lds_dwordx4 v[228:229], off
	s_mov_b32 m0, s75
	s_nop 0
	global_load_lds_dwordx4 v[230:231], off
	s_waitcnt vmcnt(8)
	s_waitcnt lgkmcnt(0)
	s_barrier
	s_waitcnt lgkmcnt(0)
	v_mfma_f32_16x16x32_bf16 v[60:63], v[152:155], v[190:193], v[60:63]
	v_mfma_f32_16x16x32_bf16 v[56:59], v[166:169], v[190:193], v[56:59]
	v_mfma_f32_16x16x32_bf16 v[44:47], v[152:155], v[202:205], v[44:47]
	v_mfma_f32_16x16x32_bf16 v[40:43], v[166:169], v[202:205], v[40:43]
	v_mfma_f32_16x16x32_bf16 v[28:31], v[152:155], v[210:213], v[28:31]
	v_mfma_f32_16x16x32_bf16 v[24:27], v[166:169], v[210:213], v[24:27]
	v_mfma_f32_16x16x32_bf16 v[12:15], v[152:155], v[218:221], v[12:15]
	v_mfma_f32_16x16x32_bf16 v[8:11], v[166:169], v[218:221], v[8:11]
	v_mfma_f32_16x16x32_bf16 v[60:63], v[162:165], v[194:197], v[60:63]
	v_mfma_f32_16x16x32_bf16 v[56:59], v[170:173], v[194:197], v[56:59]
	v_mfma_f32_16x16x32_bf16 v[44:47], v[162:165], v[206:209], v[44:47]
	v_mfma_f32_16x16x32_bf16 v[40:43], v[170:173], v[206:209], v[40:43]
	v_mfma_f32_16x16x32_bf16 v[28:31], v[162:165], v[214:217], v[28:31]
	v_mfma_f32_16x16x32_bf16 v[24:27], v[170:173], v[214:217], v[24:27]
	v_mfma_f32_16x16x32_bf16 v[12:15], v[162:165], v[222:225], v[12:15]
	v_mfma_f32_16x16x32_bf16 v[8:11], v[170:173], v[222:225], v[8:11]
	v_mfma_f32_16x16x32_bf16 v[52:55], v[174:177], v[190:193], v[52:55]
	v_mfma_f32_16x16x32_bf16 v[48:51], v[182:185], v[190:193], v[48:51]
	v_mfma_f32_16x16x32_bf16 v[36:39], v[174:177], v[202:205], v[36:39]
	v_mfma_f32_16x16x32_bf16 v[32:35], v[182:185], v[202:205], v[32:35]
	v_mfma_f32_16x16x32_bf16 v[20:23], v[174:177], v[210:213], v[20:23]
	v_mfma_f32_16x16x32_bf16 v[16:19], v[182:185], v[210:213], v[16:19]
	v_mfma_f32_16x16x32_bf16 v[4:7], v[174:177], v[218:221], v[4:7]
	v_mfma_f32_16x16x32_bf16 v[0:3], v[182:185], v[218:221], v[0:3]
	v_mfma_f32_16x16x32_bf16 v[52:55], v[178:181], v[194:197], v[52:55]
	v_mfma_f32_16x16x32_bf16 v[48:51], v[186:189], v[194:197], v[48:51]
	v_mfma_f32_16x16x32_bf16 v[36:39], v[178:181], v[206:209], v[36:39]
	v_mfma_f32_16x16x32_bf16 v[32:35], v[186:189], v[206:209], v[32:35]
	v_mfma_f32_16x16x32_bf16 v[20:23], v[178:181], v[214:217], v[20:23]
	v_mfma_f32_16x16x32_bf16 v[16:19], v[186:189], v[214:217], v[16:19]
	v_mfma_f32_16x16x32_bf16 v[4:7], v[178:181], v[222:225], v[4:7]
	v_mfma_f32_16x16x32_bf16 v[0:3], v[186:189], v[222:225], v[0:3]
	s_barrier
	s_add_i32 vcc_hi, 0, 0x18000
	v_add_u32_e32 v136, vcc_hi, v156
	s_add_i32 s14, 0, 0x1c000
	ds_read_b128 v[152:155], v136
	ds_read_b128 v[162:165], v136 offset:1024
	ds_read_b128 v[166:169], v136 offset:2048
	ds_read_b128 v[170:173], v136 offset:3072
	v_add_u32_e32 v136, s14, v156
	ds_read_b128 v[174:177], v136
	ds_read_b128 v[178:181], v136 offset:1024
	ds_read_b128 v[182:185], v136 offset:2048
	ds_read_b128 v[186:189], v136 offset:3072
	s_add_u32 s12, s82, 0x40000
	s_addc_u32 s13, s83, 0
	s_mov_b32 m0, s77
	v_lshl_add_u64 v[234:235], s[12:13], 0, v[134:135]
	ds_read_b128 v[190:193], v161 offset:32768
	ds_read_b128 v[194:197], v161 offset:33792
	ds_read_b128 v[202:205], v161 offset:34816
	ds_read_b128 v[206:209], v161 offset:35840
	ds_read_b128 v[210:213], v161 offset:36864
	ds_read_b128 v[214:217], v161 offset:37888
	ds_read_b128 v[218:221], v161 offset:38912
	ds_read_b128 v[222:225], v161 offset:39936
	global_load_lds_dwordx4 v[234:235], off
	v_lshl_add_u64 v[234:235], s[12:13], 0, v[130:131]
	s_mov_b32 m0, s87
	s_nop 0
	global_load_lds_dwordx4 v[234:235], off
	s_waitcnt vmcnt(8)
	s_waitcnt lgkmcnt(0)
	s_barrier
	s_waitcnt lgkmcnt(0)
	v_mfma_f32_16x16x32_bf16 v[124:127], v[152:155], v[190:193], v[124:127]
	v_mfma_f32_16x16x32_bf16 v[120:123], v[166:169], v[190:193], v[120:123]
	v_mfma_f32_16x16x32_bf16 v[108:111], v[152:155], v[202:205], v[108:111]
	v_mfma_f32_16x16x32_bf16 v[104:107], v[166:169], v[202:205], v[104:107]
	v_mfma_f32_16x16x32_bf16 v[92:95], v[152:155], v[210:213], v[92:95]
	v_mfma_f32_16x16x32_bf16 v[88:91], v[166:169], v[210:213], v[88:91]
	v_mfma_f32_16x16x32_bf16 v[76:79], v[152:155], v[218:221], v[76:79]
	v_mfma_f32_16x16x32_bf16 v[72:75], v[166:169], v[218:221], v[72:75]
	v_mfma_f32_16x16x32_bf16 v[124:127], v[162:165], v[194:197], v[124:127]
	v_mfma_f32_16x16x32_bf16 v[120:123], v[170:173], v[194:197], v[120:123]
	v_mfma_f32_16x16x32_bf16 v[108:111], v[162:165], v[206:209], v[108:111]
	v_mfma_f32_16x16x32_bf16 v[104:107], v[170:173], v[206:209], v[104:107]
	v_mfma_f32_16x16x32_bf16 v[92:95], v[162:165], v[214:217], v[92:95]
	v_mfma_f32_16x16x32_bf16 v[88:91], v[170:173], v[214:217], v[88:91]
	v_mfma_f32_16x16x32_bf16 v[76:79], v[162:165], v[222:225], v[76:79]
	v_mfma_f32_16x16x32_bf16 v[72:75], v[170:173], v[222:225], v[72:75]
	v_mfma_f32_16x16x32_bf16 v[116:119], v[174:177], v[190:193], v[116:119]
	v_mfma_f32_16x16x32_bf16 v[112:115], v[182:185], v[190:193], v[112:115]
	v_mfma_f32_16x16x32_bf16 v[100:103], v[174:177], v[202:205], v[100:103]
	v_mfma_f32_16x16x32_bf16 v[96:99], v[182:185], v[202:205], v[96:99]
	v_mfma_f32_16x16x32_bf16 v[84:87], v[174:177], v[210:213], v[84:87]
	v_mfma_f32_16x16x32_bf16 v[80:83], v[182:185], v[210:213], v[80:83]
	v_mfma_f32_16x16x32_bf16 v[68:71], v[174:177], v[218:221], v[68:71]
	v_mfma_f32_16x16x32_bf16 v[64:67], v[182:185], v[218:221], v[64:67]
	v_mfma_f32_16x16x32_bf16 v[116:119], v[178:181], v[194:197], v[116:119]
	v_mfma_f32_16x16x32_bf16 v[112:115], v[186:189], v[194:197], v[112:115]
	v_mfma_f32_16x16x32_bf16 v[100:103], v[178:181], v[206:209], v[100:103]
	v_mfma_f32_16x16x32_bf16 v[96:99], v[186:189], v[206:209], v[96:99]
	v_mfma_f32_16x16x32_bf16 v[84:87], v[178:181], v[214:217], v[84:87]
	v_mfma_f32_16x16x32_bf16 v[80:83], v[186:189], v[214:217], v[80:83]
	v_mfma_f32_16x16x32_bf16 v[68:71], v[178:181], v[222:225], v[68:71]
	v_mfma_f32_16x16x32_bf16 v[64:67], v[186:189], v[222:225], v[64:67]
	s_barrier
	s_add_i32 s12, vcc_hi, s3
	v_lshl_add_u64 v[198:199], v[198:199], 0, s[90:91]
	s_mov_b32 m0, s12
	ds_read_b128 v[190:193], v161 offset:49152
	ds_read_b128 v[194:197], v161 offset:50176
	ds_read_b128 v[202:205], v161 offset:51200
	ds_read_b128 v[206:209], v161 offset:52224
	ds_read_b128 v[210:213], v161 offset:53248
	ds_read_b128 v[214:217], v161 offset:54272
	ds_read_b128 v[218:221], v161 offset:55296
	ds_read_b128 v[222:225], v161 offset:56320
	global_load_lds_dwordx4 v[198:199], off
	s_add_i32 m0, s12, 0x2000
	s_add_u32 s4, s4, 0x40080
	v_lshl_add_u64 v[198:199], v[226:227], 0, s[90:91]
	s_addc_u32 s5, s5, 0
	s_add_i32 s12, s14, s3
	global_load_lds_dwordx4 v[198:199], off
	v_lshl_add_u64 v[198:199], s[4:5], 0, v[132:133]
	s_mov_b32 m0, s12
	s_nop 0
	global_load_lds_dwordx4 v[198:199], off
	v_lshl_add_u64 v[198:199], s[4:5], 0, v[128:129]
	s_add_i32 m0, s12, 0x2000
	s_nop 0
	global_load_lds_dwordx4 v[198:199], off
	v_lshl_add_u64 v[198:199], v[228:229], 0, s[90:91]
	s_mov_b32 m0, s97
	s_nop 0
	global_load_lds_dwordx4 v[198:199], off
	v_lshl_add_u64 v[198:199], v[230:231], 0, s[90:91]
	s_mov_b32 m0, s99
	s_nop 0
	global_load_lds_dwordx4 v[198:199], off
	s_waitcnt vmcnt(8)
	s_waitcnt lgkmcnt(0)
	s_barrier
	s_waitcnt lgkmcnt(0)
	v_mfma_f32_16x16x32_bf16 v[60:63], v[152:155], v[190:193], v[60:63]
	v_mfma_f32_16x16x32_bf16 v[56:59], v[166:169], v[190:193], v[56:59]
	v_mfma_f32_16x16x32_bf16 v[44:47], v[152:155], v[202:205], v[44:47]
	v_mfma_f32_16x16x32_bf16 v[40:43], v[166:169], v[202:205], v[40:43]
	v_mfma_f32_16x16x32_bf16 v[28:31], v[152:155], v[210:213], v[28:31]
	v_mfma_f32_16x16x32_bf16 v[24:27], v[166:169], v[210:213], v[24:27]
	v_mfma_f32_16x16x32_bf16 v[12:15], v[152:155], v[218:221], v[12:15]
	v_mfma_f32_16x16x32_bf16 v[8:11], v[166:169], v[218:221], v[8:11]
	v_mfma_f32_16x16x32_bf16 v[60:63], v[162:165], v[194:197], v[60:63]
	v_mfma_f32_16x16x32_bf16 v[56:59], v[170:173], v[194:197], v[56:59]
	v_mfma_f32_16x16x32_bf16 v[44:47], v[162:165], v[206:209], v[44:47]
	v_mfma_f32_16x16x32_bf16 v[40:43], v[170:173], v[206:209], v[40:43]
	v_mfma_f32_16x16x32_bf16 v[28:31], v[162:165], v[214:217], v[28:31]
	v_mfma_f32_16x16x32_bf16 v[24:27], v[170:173], v[214:217], v[24:27]
	v_mfma_f32_16x16x32_bf16 v[12:15], v[162:165], v[222:225], v[12:15]
	v_mfma_f32_16x16x32_bf16 v[8:11], v[170:173], v[222:225], v[8:11]
	v_mfma_f32_16x16x32_bf16 v[52:55], v[174:177], v[190:193], v[52:55]
	v_mfma_f32_16x16x32_bf16 v[48:51], v[182:185], v[190:193], v[48:51]
	v_mfma_f32_16x16x32_bf16 v[36:39], v[174:177], v[202:205], v[36:39]
	v_mfma_f32_16x16x32_bf16 v[32:35], v[182:185], v[202:205], v[32:35]
	v_mfma_f32_16x16x32_bf16 v[20:23], v[174:177], v[210:213], v[20:23]
	v_mfma_f32_16x16x32_bf16 v[16:19], v[182:185], v[210:213], v[16:19]
	v_mfma_f32_16x16x32_bf16 v[4:7], v[174:177], v[218:221], v[4:7]
	v_mfma_f32_16x16x32_bf16 v[0:3], v[182:185], v[218:221], v[0:3]
	v_mfma_f32_16x16x32_bf16 v[52:55], v[178:181], v[194:197], v[52:55]
	v_mfma_f32_16x16x32_bf16 v[48:51], v[186:189], v[194:197], v[48:51]
	v_mfma_f32_16x16x32_bf16 v[36:39], v[178:181], v[206:209], v[36:39]
	v_mfma_f32_16x16x32_bf16 v[32:35], v[186:189], v[206:209], v[32:35]
	v_mfma_f32_16x16x32_bf16 v[20:23], v[178:181], v[214:217], v[20:23]
	v_mfma_f32_16x16x32_bf16 v[16:19], v[186:189], v[214:217], v[16:19]
	v_mfma_f32_16x16x32_bf16 v[4:7], v[178:181], v[222:225], v[4:7]
	v_mfma_f32_16x16x32_bf16 v[0:3], v[186:189], v[222:225], v[0:3]
	s_barrier
	s_add_i32 vcc_lo, vcc_lo, 2
	s_add_u32 s0, s0, 0x100
	s_addc_u32 s1, s1, 0
	s_add_u32 s53, s53, 0x100
	s_addc_u32 s79, s79, 0
	s_cmp_gt_u32 vcc_lo, 13
	s_cbranch_scc0 .LBB0_180
	s_setprio 0
	s_and_b64 vcc, exec, s[92:93]
	s_cbranch_vccnz .LBB0_184
	s_cmp_gt_i32 s11, 3
	s_mov_b64 s[0:1], -1
	s_cbranch_scc1 .LBB0_185

.LBB0_305:
	s_ashr_i32 s89, s88, 31
	s_lshl_b64 s[16:17], s[88:89], 19
	s_add_u32 s90, s80, s16
	s_addc_u32 s91, s81, s17
	s_ashr_i32 s87, s86, 31
	s_lshl_b64 s[16:17], s[86:87], 19
	s_add_u32 s92, s39, s16
	s_addc_u32 s93, s49, s17
	s_and_b64 s[16:17], s[6:7], exec
	s_cselect_b32 s11, s91, s9
	s_cselect_b32 s87, s90, s8
	s_cselect_b32 s89, s93, s41
	s_cselect_b32 s95, s92, s40
	s_add_u32 s8, s8, 0x40080
	s_addc_u32 s9, s9, 0
	s_add_u32 vcc_lo, s40, 0x100
	v_mov_b32_e32 v0, 0
	s_addc_u32 vcc_hi, s41, 0
	s_mov_b32 s16, -2
	v_mov_b32_e32 v1, v0
	v_mov_b32_e32 v2, v0
	v_mov_b32_e32 v3, v0
	v_mov_b32_e32 v8, v0
	v_mov_b32_e32 v9, v0
	v_mov_b32_e32 v10, v0
	v_mov_b32_e32 v11, v0
	v_mov_b32_e32 v16, v0
	v_mov_b32_e32 v17, v0
	v_mov_b32_e32 v18, v0
	v_mov_b32_e32 v19, v0
	v_mov_b32_e32 v24, v0
	v_mov_b32_e32 v25, v0
	v_mov_b32_e32 v26, v0
	v_mov_b32_e32 v27, v0
	v_mov_b32_e32 v32, v0
	v_mov_b32_e32 v33, v0
	v_mov_b32_e32 v34, v0
	v_mov_b32_e32 v35, v0
	v_mov_b32_e32 v40, v0
	v_mov_b32_e32 v41, v0
	v_mov_b32_e32 v42, v0
	v_mov_b32_e32 v43, v0
	v_mov_b32_e32 v48, v0
	v_mov_b32_e32 v49, v0
	v_mov_b32_e32 v50, v0
	v_mov_b32_e32 v51, v0
	v_mov_b32_e32 v56, v0
	v_mov_b32_e32 v57, v0
	v_mov_b32_e32 v58, v0
	v_mov_b32_e32 v59, v0
	v_mov_b32_e32 v4, v0
	v_mov_b32_e32 v5, v0
	v_mov_b32_e32 v6, v0
	v_mov_b32_e32 v7, v0
	v_mov_b32_e32 v12, v0
	v_mov_b32_e32 v13, v0
	v_mov_b32_e32 v14, v0
	v_mov_b32_e32 v15, v0
	v_mov_b32_e32 v20, v0
	v_mov_b32_e32 v21, v0
	v_mov_b32_e32 v22, v0
	v_mov_b32_e32 v23, v0
	v_mov_b32_e32 v28, v0
	v_mov_b32_e32 v29, v0
	v_mov_b32_e32 v30, v0
	v_mov_b32_e32 v31, v0
	v_mov_b32_e32 v36, v0
	v_mov_b32_e32 v37, v0
	v_mov_b32_e32 v38, v0
	v_mov_b32_e32 v39, v0
	v_mov_b32_e32 v44, v0
	v_mov_b32_e32 v45, v0
	v_mov_b32_e32 v46, v0
	v_mov_b32_e32 v47, v0
	v_mov_b32_e32 v52, v0
	v_mov_b32_e32 v53, v0
	v_mov_b32_e32 v54, v0
	v_mov_b32_e32 v55, v0
	v_mov_b32_e32 v60, v0
	v_mov_b32_e32 v61, v0
	v_mov_b32_e32 v62, v0
	v_mov_b32_e32 v63, v0
	v_mov_b32_e32 v64, v0
	v_mov_b32_e32 v65, v0
	v_mov_b32_e32 v66, v0
	v_mov_b32_e32 v67, v0
	v_mov_b32_e32 v72, v0
	v_mov_b32_e32 v73, v0
	v_mov_b32_e32 v74, v0
	v_mov_b32_e32 v75, v0
	v_mov_b32_e32 v80, v0
	v_mov_b32_e32 v81, v0
	v_mov_b32_e32 v82, v0
	v_mov_b32_e32 v83, v0
	v_mov_b32_e32 v88, v0
	v_mov_b32_e32 v89, v0
	v_mov_b32_e32 v90, v0
	v_mov_b32_e32 v91, v0
	v_mov_b32_e32 v96, v0
	v_mov_b32_e32 v97, v0
	v_mov_b32_e32 v98, v0
	v_mov_b32_e32 v99, v0
	v_mov_b32_e32 v104, v0
	v_mov_b32_e32 v105, v0
	v_mov_b32_e32 v106, v0
	v_mov_b32_e32 v107, v0
	v_mov_b32_e32 v120, v0
	v_mov_b32_e32 v121, v0
	v_mov_b32_e32 v122, v0
	v_mov_b32_e32 v123, v0
	v_mov_b32_e32 v128, v0
	v_mov_b32_e32 v129, v0
	v_mov_b32_e32 v130, v0
	v_mov_b32_e32 v131, v0
	v_mov_b32_e32 v68, v0
	v_mov_b32_e32 v69, v0
	v_mov_b32_e32 v70, v0
	v_mov_b32_e32 v71, v0
	v_mov_b32_e32 v76, v0
	v_mov_b32_e32 v77, v0
	v_mov_b32_e32 v78, v0
	v_mov_b32_e32 v79, v0
	v_mov_b32_e32 v84, v0
	v_mov_b32_e32 v85, v0
	v_mov_b32_e32 v86, v0
	v_mov_b32_e32 v87, v0
	v_mov_b32_e32 v92, v0
	v_mov_b32_e32 v93, v0
	v_mov_b32_e32 v94, v0
	v_mov_b32_e32 v95, v0
	v_mov_b32_e32 v100, v0
	v_mov_b32_e32 v101, v0
	v_mov_b32_e32 v102, v0
	v_mov_b32_e32 v103, v0
	v_mov_b32_e32 v108, v0
	v_mov_b32_e32 v109, v0
	v_mov_b32_e32 v110, v0
	v_mov_b32_e32 v111, v0
	v_mov_b32_e32 v124, v0
	v_mov_b32_e32 v125, v0
	v_mov_b32_e32 v126, v0
	v_mov_b32_e32 v127, v0
	v_mov_b32_e32 v132, v0
	v_mov_b32_e32 v133, v0
	v_mov_b32_e32 v134, v0
	v_mov_b32_e32 v135, v0
	v_readfirstlane_b32 s32, v201
	s_nop 3
	s_cmp_lt_u32 s32, 0x100
	s_cbranch_scc1 .Lprio_skip1
	s_setprio 1
.Lprio_skip1:
.LBB0_306:
	ds_read_b128 v[112:115], v213
	ds_read_b128 v[116:119], v213 offset:1024
	ds_read_b128 v[136:139], v213 offset:2048
	ds_read_b128 v[140:143], v213 offset:3072
	ds_read_b128 v[144:147], v243
	ds_read_b128 v[148:151], v243 offset:1024
	ds_read_b128 v[152:155], v243 offset:2048
	ds_read_b128 v[156:159], v243 offset:3072
	s_add_u32 s17, s8, 0xfffc0080
	s_addc_u32 s26, s9, -1
	s_cmp_eq_u32 s16, 12
	s_cselect_b32 s73, s11, s26
	s_cselect_b32 s72, s87, s17
	s_cselect_b32 s41, s89, vcc_hi
	s_cselect_b32 s40, s95, vcc_lo
	v_lshl_add_u64 v[192:193], s[8:9], 0, v[220:221]
	s_add_i32 m0, s55, 0xc000
	ds_read_b128 v[160:163], v244
	ds_read_b128 v[164:167], v244 offset:1024
	ds_read_b128 v[168:171], v244 offset:2048
	ds_read_b128 v[172:175], v244 offset:3072
	ds_read_b128 v[176:179], v244 offset:4096
	ds_read_b128 v[180:183], v244 offset:5120
	ds_read_b128 v[184:187], v244 offset:6144
	ds_read_b128 v[188:191], v244 offset:7168
	global_load_lds_dwordx4 v[192:193], off
	v_lshl_add_u64 v[192:193], s[8:9], 0, v[222:223]
	s_add_i32 m0, s55, 0xe000
	s_nop 0
	global_load_lds_dwordx4 v[192:193], off
	s_waitcnt vmcnt(8)
	s_waitcnt lgkmcnt(0)
	s_barrier
	s_waitcnt lgkmcnt(0)
	v_mfma_f32_16x16x32_bf16 v[132:135], v[112:115], v[160:163], v[132:135]
	v_mfma_f32_16x16x32_bf16 v[124:127], v[136:139], v[160:163], v[124:127]
	v_mfma_f32_16x16x32_bf16 v[108:111], v[112:115], v[168:171], v[108:111]
	v_mfma_f32_16x16x32_bf16 v[100:103], v[136:139], v[168:171], v[100:103]
	v_mfma_f32_16x16x32_bf16 v[92:95], v[112:115], v[176:179], v[92:95]
	v_mfma_f32_16x16x32_bf16 v[84:87], v[136:139], v[176:179], v[84:87]
	v_mfma_f32_16x16x32_bf16 v[76:79], v[112:115], v[184:187], v[76:79]
	v_mfma_f32_16x16x32_bf16 v[68:71], v[136:139], v[184:187], v[68:71]
	v_mfma_f32_16x16x32_bf16 v[132:135], v[116:119], v[164:167], v[132:135]
	v_mfma_f32_16x16x32_bf16 v[124:127], v[140:143], v[164:167], v[124:127]
	v_mfma_f32_16x16x32_bf16 v[108:111], v[116:119], v[172:175], v[108:111]
	v_mfma_f32_16x16x32_bf16 v[100:103], v[140:143], v[172:175], v[100:103]
	v_mfma_f32_16x16x32_bf16 v[92:95], v[116:119], v[180:183], v[92:95]
	v_mfma_f32_16x16x32_bf16 v[84:87], v[140:143], v[180:183], v[84:87]
	v_mfma_f32_16x16x32_bf16 v[76:79], v[116:119], v[188:191], v[76:79]
	v_mfma_f32_16x16x32_bf16 v[68:71], v[140:143], v[188:191], v[68:71]
	v_mfma_f32_16x16x32_bf16 v[128:131], v[144:147], v[160:163], v[128:131]
	v_mfma_f32_16x16x32_bf16 v[120:123], v[152:155], v[160:163], v[120:123]
	v_mfma_f32_16x16x32_bf16 v[104:107], v[144:147], v[168:171], v[104:107]
	v_mfma_f32_16x16x32_bf16 v[96:99], v[152:155], v[168:171], v[96:99]
	v_mfma_f32_16x16x32_bf16 v[88:91], v[144:147], v[176:179], v[88:91]
	v_mfma_f32_16x16x32_bf16 v[80:83], v[152:155], v[176:179], v[80:83]
	v_mfma_f32_16x16x32_bf16 v[72:75], v[144:147], v[184:187], v[72:75]
	v_mfma_f32_16x16x32_bf16 v[64:67], v[152:155], v[184:187], v[64:67]
	v_mfma_f32_16x16x32_bf16 v[128:131], v[148:151], v[164:167], v[128:131]
	v_mfma_f32_16x16x32_bf16 v[120:123], v[156:159], v[164:167], v[120:123]
	v_mfma_f32_16x16x32_bf16 v[104:107], v[148:151], v[172:175], v[104:107]
	v_mfma_f32_16x16x32_bf16 v[96:99], v[156:159], v[172:175], v[96:99]
	v_mfma_f32_16x16x32_bf16 v[88:91], v[148:151], v[180:183], v[88:91]
	v_mfma_f32_16x16x32_bf16 v[80:83], v[156:159], v[180:183], v[80:83]
	v_mfma_f32_16x16x32_bf16 v[72:75], v[148:151], v[188:191], v[72:75]
	v_mfma_f32_16x16x32_bf16 v[64:67], v[156:159], v[188:191], v[64:67]
	s_barrier
	s_add_i32 s17, s3, s53
	v_lshl_add_u64 v[192:193], s[40:41], 0, v[204:205]
	s_mov_b32 m0, s17
	ds_read_b128 v[160:163], v244 offset:16384
	ds_read_b128 v[164:167], v244 offset:17408
	ds_read_b128 v[168:171], v244 offset:18432
	ds_read_b128 v[172:175], v244 offset:19456
	ds_read_b128 v[176:179], v244 offset:20480
	ds_read_b128 v[180:183], v244 offset:21504
	ds_read_b128 v[184:187], v244 offset:22528
	ds_read_b128 v[188:191], v244 offset:23552
	global_load_lds_dwordx4 v[192:193], off
	s_add_i32 m0, s17, 0x2000
	s_add_u32 s26, s40, 0x40000
	v_lshl_add_u64 v[194:195], s[40:41], 0, v[208:209]
	s_addc_u32 s27, s41, 0
	s_add_i32 s17, s33, s53
	global_load_lds_dwordx4 v[194:195], off
	v_lshl_add_u64 v[196:197], s[26:27], 0, v[204:205]
	s_mov_b32 m0, s17
	v_lshl_add_u64 v[198:199], s[72:73], 0, v[206:207]
	global_load_lds_dwordx4 v[196:197], off
	v_lshl_add_u64 v[196:197], s[26:27], 0, v[208:209]
	s_add_i32 m0, s17, 0x2000
	s_nop 0
	global_load_lds_dwordx4 v[196:197], off
	v_lshl_add_u64 v[196:197], s[72:73], 0, v[202:203]
	s_mov_b32 m0, s55
	s_nop 0
	global_load_lds_dwordx4 v[196:197], off
	s_mov_b32 m0, s63
	s_nop 0
	global_load_lds_dwordx4 v[198:199], off
	s_waitcnt vmcnt(8)
	s_waitcnt lgkmcnt(0)
	s_barrier
	s_waitcnt lgkmcnt(0)
	v_mfma_f32_16x16x32_bf16 v[60:63], v[112:115], v[160:163], v[60:63]
	v_mfma_f32_16x16x32_bf16 v[52:55], v[136:139], v[160:163], v[52:55]
	v_mfma_f32_16x16x32_bf16 v[44:47], v[112:115], v[168:171], v[44:47]
	v_mfma_f32_16x16x32_bf16 v[36:39], v[136:139], v[168:171], v[36:39]
	v_mfma_f32_16x16x32_bf16 v[28:31], v[112:115], v[176:179], v[28:31]
	v_mfma_f32_16x16x32_bf16 v[20:23], v[136:139], v[176:179], v[20:23]
	v_mfma_f32_16x16x32_bf16 v[12:15], v[112:115], v[184:187], v[12:15]
	v_mfma_f32_16x16x32_bf16 v[4:7], v[136:139], v[184:187], v[4:7]
	v_mfma_f32_16x16x32_bf16 v[60:63], v[116:119], v[164:167], v[60:63]
	v_mfma_f32_16x16x32_bf16 v[52:55], v[140:143], v[164:167], v[52:55]
	v_mfma_f32_16x16x32_bf16 v[44:47], v[116:119], v[172:175], v[44:47]
	v_mfma_f32_16x16x32_bf16 v[36:39], v[140:143], v[172:175], v[36:39]
	v_mfma_f32_16x16x32_bf16 v[28:31], v[116:119], v[180:183], v[28:31]
	v_mfma_f32_16x16x32_bf16 v[20:23], v[140:143], v[180:183], v[20:23]
	v_mfma_f32_16x16x32_bf16 v[12:15], v[116:119], v[188:191], v[12:15]
	v_mfma_f32_16x16x32_bf16 v[4:7], v[140:143], v[188:191], v[4:7]
	v_mfma_f32_16x16x32_bf16 v[56:59], v[144:147], v[160:163], v[56:59]
	v_mfma_f32_16x16x32_bf16 v[48:51], v[152:155], v[160:163], v[48:51]
	v_mfma_f32_16x16x32_bf16 v[40:43], v[144:147], v[168:171], v[40:43]
	v_mfma_f32_16x16x32_bf16 v[32:35], v[152:155], v[168:171], v[32:35]
	v_mfma_f32_16x16x32_bf16 v[24:27], v[144:147], v[176:179], v[24:27]
	v_mfma_f32_16x16x32_bf16 v[16:19], v[152:155], v[176:179], v[16:19]
	v_mfma_f32_16x16x32_bf16 v[8:11], v[144:147], v[184:187], v[8:11]
	v_mfma_f32_16x16x32_bf16 v[0:3], v[152:155], v[184:187], v[0:3]
	v_mfma_f32_16x16x32_bf16 v[56:59], v[148:151], v[164:167], v[56:59]
	v_mfma_f32_16x16x32_bf16 v[48:51], v[156:159], v[164:167], v[48:51]
	v_mfma_f32_16x16x32_bf16 v[40:43], v[148:151], v[172:175], v[40:43]
	v_mfma_f32_16x16x32_bf16 v[32:35], v[156:159], v[172:175], v[32:35]
	v_mfma_f32_16x16x32_bf16 v[24:27], v[148:151], v[180:183], v[24:27]
	v_mfma_f32_16x16x32_bf16 v[16:19], v[156:159], v[180:183], v[16:19]
	v_mfma_f32_16x16x32_bf16 v[8:11], v[148:151], v[188:191], v[8:11]
	v_mfma_f32_16x16x32_bf16 v[0:3], v[156:159], v[188:191], v[0:3]
	s_barrier
	s_add_i32 s17, 0, 0x18000
	s_add_i32 s28, 0, 0x1c000
	v_add_u32_e32 v140, s17, v235
	v_add_u32_e32 v156, s28, v235
	ds_read_b128 v[112:115], v140
	ds_read_b128 v[116:119], v140 offset:1024
	ds_read_b128 v[136:139], v140 offset:2048
	ds_read_b128 v[140:143], v140 offset:3072
	ds_read_b128 v[144:147], v156
	ds_read_b128 v[148:151], v156 offset:1024
	ds_read_b128 v[152:155], v156 offset:2048
	ds_read_b128 v[156:159], v156 offset:3072
	s_add_u32 s26, s72, 0x40000
	s_addc_u32 s27, s73, 0
	s_mov_b32 m0, s74
	v_lshl_add_u64 v[228:229], s[26:27], 0, v[202:203]
	ds_read_b128 v[160:163], v244 offset:32768
	ds_read_b128 v[164:167], v244 offset:33792
	ds_read_b128 v[168:171], v244 offset:34816
	ds_read_b128 v[172:175], v244 offset:35840
	ds_read_b128 v[176:179], v244 offset:36864
	ds_read_b128 v[180:183], v244 offset:37888
	ds_read_b128 v[184:187], v244 offset:38912
	ds_read_b128 v[188:191], v244 offset:39936
	global_load_lds_dwordx4 v[228:229], off
	v_lshl_add_u64 v[228:229], s[26:27], 0, v[206:207]
	s_mov_b32 m0, s76
	s_nop 0
	global_load_lds_dwordx4 v[228:229], off
	s_waitcnt vmcnt(8)
	s_waitcnt lgkmcnt(0)
	s_barrier
	s_waitcnt lgkmcnt(0)
	v_mfma_f32_16x16x32_bf16 v[132:135], v[112:115], v[160:163], v[132:135]
	v_mfma_f32_16x16x32_bf16 v[124:127], v[136:139], v[160:163], v[124:127]
	v_mfma_f32_16x16x32_bf16 v[108:111], v[112:115], v[168:171], v[108:111]
	v_mfma_f32_16x16x32_bf16 v[100:103], v[136:139], v[168:171], v[100:103]
	v_mfma_f32_16x16x32_bf16 v[92:95], v[112:115], v[176:179], v[92:95]
	v_mfma_f32_16x16x32_bf16 v[84:87], v[136:139], v[176:179], v[84:87]
	v_mfma_f32_16x16x32_bf16 v[76:79], v[112:115], v[184:187], v[76:79]
	v_mfma_f32_16x16x32_bf16 v[68:71], v[136:139], v[184:187], v[68:71]
	v_mfma_f32_16x16x32_bf16 v[132:135], v[116:119], v[164:167], v[132:135]
	v_mfma_f32_16x16x32_bf16 v[124:127], v[140:143], v[164:167], v[124:127]
	v_mfma_f32_16x16x32_bf16 v[108:111], v[116:119], v[172:175], v[108:111]
	v_mfma_f32_16x16x32_bf16 v[100:103], v[140:143], v[172:175], v[100:103]
	v_mfma_f32_16x16x32_bf16 v[92:95], v[116:119], v[180:183], v[92:95]
	v_mfma_f32_16x16x32_bf16 v[84:87], v[140:143], v[180:183], v[84:87]
	v_mfma_f32_16x16x32_bf16 v[76:79], v[116:119], v[188:191], v[76:79]
	v_mfma_f32_16x16x32_bf16 v[68:71], v[140:143], v[188:191], v[68:71]
	v_mfma_f32_16x16x32_bf16 v[128:131], v[144:147], v[160:163], v[128:131]
	v_mfma_f32_16x16x32_bf16 v[120:123], v[152:155], v[160:163], v[120:123]
	v_mfma_f32_16x16x32_bf16 v[104:107], v[144:147], v[168:171], v[104:107]
	v_mfma_f32_16x16x32_bf16 v[96:99], v[152:155], v[168:171], v[96:99]
	v_mfma_f32_16x16x32_bf16 v[88:91], v[144:147], v[176:179], v[88:91]
	v_mfma_f32_16x16x32_bf16 v[80:83], v[152:155], v[176:179], v[80:83]
	v_mfma_f32_16x16x32_bf16 v[72:75], v[144:147], v[184:187], v[72:75]
	v_mfma_f32_16x16x32_bf16 v[64:67], v[152:155], v[184:187], v[64:67]
	v_mfma_f32_16x16x32_bf16 v[128:131], v[148:151], v[164:167], v[128:131]
	v_mfma_f32_16x16x32_bf16 v[120:123], v[156:159], v[164:167], v[120:123]
	v_mfma_f32_16x16x32_bf16 v[104:107], v[148:151], v[172:175], v[104:107]
	v_mfma_f32_16x16x32_bf16 v[96:99], v[156:159], v[172:175], v[96:99]
	v_mfma_f32_16x16x32_bf16 v[88:91], v[148:151], v[180:183], v[88:91]
	v_mfma_f32_16x16x32_bf16 v[80:83], v[156:159], v[180:183], v[80:83]
	v_mfma_f32_16x16x32_bf16 v[72:75], v[148:151], v[188:191], v[72:75]
	v_mfma_f32_16x16x32_bf16 v[64:67], v[156:159], v[188:191], v[64:67]
	s_barrier
	s_add_i32 s17, s17, s53
	v_lshl_add_u64 v[192:193], v[192:193], 0, s[20:21]
	s_mov_b32 m0, s17
	ds_read_b128 v[160:163], v244 offset:49152
	ds_read_b128 v[164:167], v244 offset:50176
	ds_read_b128 v[168:171], v244 offset:51200
	ds_read_b128 v[172:175], v244 offset:52224
	ds_read_b128 v[176:179], v244 offset:53248
	ds_read_b128 v[180:183], v244 offset:54272
	ds_read_b128 v[184:187], v244 offset:55296
	ds_read_b128 v[188:191], v244 offset:56320
	global_load_lds_dwordx4 v[192:193], off
	s_add_i32 m0, s17, 0x2000
	s_add_u32 s26, s40, 0x40080
	v_lshl_add_u64 v[192:193], v[194:195], 0, s[20:21]
	s_addc_u32 s27, s41, 0
	s_add_i32 s17, s28, s53
	global_load_lds_dwordx4 v[192:193], off
	v_lshl_add_u64 v[192:193], s[26:27], 0, v[204:205]
	s_mov_b32 m0, s17
	s_nop 0
	global_load_lds_dwordx4 v[192:193], off
	v_lshl_add_u64 v[192:193], s[26:27], 0, v[208:209]
	s_add_i32 m0, s17, 0x2000
	s_nop 0
	global_load_lds_dwordx4 v[192:193], off
	v_lshl_add_u64 v[192:193], v[196:197], 0, s[20:21]
	s_mov_b32 m0, s78
	s_nop 0
	global_load_lds_dwordx4 v[192:193], off
	v_lshl_add_u64 v[192:193], v[198:199], 0, s[20:21]
	s_mov_b32 m0, s79
	s_nop 0
	global_load_lds_dwordx4 v[192:193], off
	s_waitcnt vmcnt(8)
	s_waitcnt lgkmcnt(0)
	s_barrier
	s_waitcnt lgkmcnt(0)
	v_mfma_f32_16x16x32_bf16 v[60:63], v[112:115], v[160:163], v[60:63]
	v_mfma_f32_16x16x32_bf16 v[52:55], v[136:139], v[160:163], v[52:55]
	v_mfma_f32_16x16x32_bf16 v[44:47], v[112:115], v[168:171], v[44:47]
	v_mfma_f32_16x16x32_bf16 v[36:39], v[136:139], v[168:171], v[36:39]
	v_mfma_f32_16x16x32_bf16 v[28:31], v[112:115], v[176:179], v[28:31]
	v_mfma_f32_16x16x32_bf16 v[20:23], v[136:139], v[176:179], v[20:23]
	v_mfma_f32_16x16x32_bf16 v[12:15], v[112:115], v[184:187], v[12:15]
	v_mfma_f32_16x16x32_bf16 v[4:7], v[136:139], v[184:187], v[4:7]
	v_mfma_f32_16x16x32_bf16 v[60:63], v[116:119], v[164:167], v[60:63]
	v_mfma_f32_16x16x32_bf16 v[52:55], v[140:143], v[164:167], v[52:55]
	v_mfma_f32_16x16x32_bf16 v[44:47], v[116:119], v[172:175], v[44:47]
	v_mfma_f32_16x16x32_bf16 v[36:39], v[140:143], v[172:175], v[36:39]
	v_mfma_f32_16x16x32_bf16 v[28:31], v[116:119], v[180:183], v[28:31]
	v_mfma_f32_16x16x32_bf16 v[20:23], v[140:143], v[180:183], v[20:23]
	v_mfma_f32_16x16x32_bf16 v[12:15], v[116:119], v[188:191], v[12:15]
	v_mfma_f32_16x16x32_bf16 v[4:7], v[140:143], v[188:191], v[4:7]
	v_mfma_f32_16x16x32_bf16 v[56:59], v[144:147], v[160:163], v[56:59]
	v_mfma_f32_16x16x32_bf16 v[48:51], v[152:155], v[160:163], v[48:51]
	v_mfma_f32_16x16x32_bf16 v[40:43], v[144:147], v[168:171], v[40:43]
	v_mfma_f32_16x16x32_bf16 v[32:35], v[152:155], v[168:171], v[32:35]
	v_mfma_f32_16x16x32_bf16 v[24:27], v[144:147], v[176:179], v[24:27]
	v_mfma_f32_16x16x32_bf16 v[16:19], v[152:155], v[176:179], v[16:19]
	v_mfma_f32_16x16x32_bf16 v[8:11], v[144:147], v[184:187], v[8:11]
	v_mfma_f32_16x16x32_bf16 v[0:3], v[152:155], v[184:187], v[0:3]
	v_mfma_f32_16x16x32_bf16 v[56:59], v[148:151], v[164:167], v[56:59]
	v_mfma_f32_16x16x32_bf16 v[48:51], v[156:159], v[164:167], v[48:51]
	v_mfma_f32_16x16x32_bf16 v[40:43], v[148:151], v[172:175], v[40:43]
	v_mfma_f32_16x16x32_bf16 v[32:35], v[156:159], v[172:175], v[32:35]
	v_mfma_f32_16x16x32_bf16 v[24:27], v[148:151], v[180:183], v[24:27]
	v_mfma_f32_16x16x32_bf16 v[16:19], v[156:159], v[180:183], v[16:19]
	v_mfma_f32_16x16x32_bf16 v[8:11], v[148:151], v[188:191], v[8:11]
	v_mfma_f32_16x16x32_bf16 v[0:3], v[156:159], v[188:191], v[0:3]
	s_barrier
	s_add_i32 s16, s16, 2
	s_add_u32 s8, s8, 0x100
	s_addc_u32 s9, s9, 0
	s_add_u32 vcc_lo, vcc_lo, 0x100
	s_addc_u32 vcc_hi, vcc_hi, 0
	s_cmp_gt_u32 s16, 13
	s_cbranch_scc0 .LBB0_306
	s_setprio 0
	s_and_b64 vcc, exec, s[22:23]
	s_cbranch_vccnz .LBB0_311
	s_lshl_b32 s87, s10, 7
	s_cmp_gt_i32 s10, 7
	s_mov_b64 s[8:9], -1
	s_cbranch_scc1 .LBB0_312

.LBB0_494:
	s_add_u32 s27, s30, 0x100
	s_addc_u32 s55, s31, 0
	s_ashr_i32 s23, s22, 31
	s_lshl_b64 s[24:25], s[22:23], 20
	s_add_u32 s28, s12, s24
	s_addc_u32 s29, s13, s25
	s_ashr_i32 s21, s20, 31
	s_lshl_b64 s[24:25], s[20:21], 20
	s_add_u32 s24, s88, s24
	s_addc_u32 s25, s89, s25
	s_and_b64 s[34:35], s[4:5], exec
	s_cselect_b32 s21, s29, s17
	s_cselect_b32 s23, s28, s16
	s_cselect_b32 s56, s25, s31
	s_cselect_b32 s57, s24, s30
	v_lshl_add_u64 v[140:141], s[16:17], 0, v[132:133]
	v_lshl_add_u64 v[142:143], s[16:17], 0, v[134:135]
	s_mov_b32 s58, -2
	s_mov_b64 s[30:31], 0
	v_readfirstlane_b32 s32, v201
	s_nop 3
	s_cmp_lt_u32 s32, 0x100
	s_cbranch_scc1 .Lprio_skip2
	s_setprio 1
.Lprio_skip2:
.LBB0_495:
	v_add_u32_e32 v147, s53, v145
	ds_read_b128 v[148:151], v147
	ds_read_b128 v[152:155], v147 offset:1024
	ds_read_b128 v[156:159], v147 offset:2048
	ds_read_b128 v[160:163], v147 offset:3072
	v_add_u32_e32 v147, s54, v145
	s_add_u32 s34, s16, s30
	ds_read_b128 v[164:167], v147
	ds_read_b128 v[172:175], v147 offset:1024
	ds_read_b128 v[176:179], v147 offset:2048
	ds_read_b128 v[180:183], v147 offset:3072
	s_addc_u32 s35, s17, s31
	s_add_u32 s34, s34, 0x100
	s_addc_u32 s35, s35, 0
	s_add_u32 s59, s27, s30
	s_addc_u32 s60, s55, s31
	s_cmpk_eq_i32 s30, 0xf00
	s_cselect_b32 s37, s21, s35
	s_cselect_b32 s36, s23, s34
	s_cselect_b32 s35, s56, s60
	s_cselect_b32 s34, s57, s59
	v_lshl_add_u64 v[168:169], v[140:141], 0, s[30:31]
	s_add_i32 m0, s40, 0xc000
	ds_read_b128 v[184:187], v146
	ds_read_b128 v[188:191], v146 offset:1024
	ds_read_b128 v[192:195], v146 offset:2048
	ds_read_b128 v[196:199], v146 offset:3072
	ds_read_b128 v[202:205], v146 offset:4096
	ds_read_b128 v[206:209], v146 offset:5120
	ds_read_b128 v[210:213], v146 offset:6144
	ds_read_b128 v[214:217], v146 offset:7168
	global_load_lds_dwordx4 v[168:169], off
	v_lshl_add_u64 v[168:169], v[142:143], 0, s[30:31]
	s_add_i32 m0, s40, 0xe000
	s_nop 0
	global_load_lds_dwordx4 v[168:169], off
	s_waitcnt vmcnt(8)
	s_waitcnt lgkmcnt(0)
	s_barrier
	s_waitcnt lgkmcnt(0)
	v_mfma_f32_16x16x32_bf16 v[124:127], v[148:151], v[184:187], v[124:127]
	v_mfma_f32_16x16x32_bf16 v[120:123], v[156:159], v[184:187], v[120:123]
	v_mfma_f32_16x16x32_bf16 v[108:111], v[148:151], v[192:195], v[108:111]
	v_mfma_f32_16x16x32_bf16 v[104:107], v[156:159], v[192:195], v[104:107]
	v_mfma_f32_16x16x32_bf16 v[92:95], v[148:151], v[202:205], v[92:95]
	v_mfma_f32_16x16x32_bf16 v[88:91], v[156:159], v[202:205], v[88:91]
	v_mfma_f32_16x16x32_bf16 v[76:79], v[148:151], v[210:213], v[76:79]
	v_mfma_f32_16x16x32_bf16 v[72:75], v[156:159], v[210:213], v[72:75]
	v_mfma_f32_16x16x32_bf16 v[124:127], v[152:155], v[188:191], v[124:127]
	v_mfma_f32_16x16x32_bf16 v[120:123], v[160:163], v[188:191], v[120:123]
	v_mfma_f32_16x16x32_bf16 v[108:111], v[152:155], v[196:199], v[108:111]
	v_mfma_f32_16x16x32_bf16 v[104:107], v[160:163], v[196:199], v[104:107]
	v_mfma_f32_16x16x32_bf16 v[92:95], v[152:155], v[206:209], v[92:95]
	v_mfma_f32_16x16x32_bf16 v[88:91], v[160:163], v[206:209], v[88:91]
	v_mfma_f32_16x16x32_bf16 v[76:79], v[152:155], v[214:217], v[76:79]
	v_mfma_f32_16x16x32_bf16 v[72:75], v[160:163], v[214:217], v[72:75]
	v_mfma_f32_16x16x32_bf16 v[116:119], v[164:167], v[184:187], v[116:119]
	v_mfma_f32_16x16x32_bf16 v[112:115], v[176:179], v[184:187], v[112:115]
	v_mfma_f32_16x16x32_bf16 v[100:103], v[164:167], v[192:195], v[100:103]
	v_mfma_f32_16x16x32_bf16 v[96:99], v[176:179], v[192:195], v[96:99]
	v_mfma_f32_16x16x32_bf16 v[84:87], v[164:167], v[202:205], v[84:87]
	v_mfma_f32_16x16x32_bf16 v[80:83], v[176:179], v[202:205], v[80:83]
	v_mfma_f32_16x16x32_bf16 v[68:71], v[164:167], v[210:213], v[68:71]
	v_mfma_f32_16x16x32_bf16 v[64:67], v[176:179], v[210:213], v[64:67]
	v_mfma_f32_16x16x32_bf16 v[116:119], v[172:175], v[188:191], v[116:119]
	v_mfma_f32_16x16x32_bf16 v[112:115], v[180:183], v[188:191], v[112:115]
	v_mfma_f32_16x16x32_bf16 v[100:103], v[172:175], v[196:199], v[100:103]
	v_mfma_f32_16x16x32_bf16 v[96:99], v[180:183], v[196:199], v[96:99]
	v_mfma_f32_16x16x32_bf16 v[84:87], v[172:175], v[206:209], v[84:87]
	v_mfma_f32_16x16x32_bf16 v[80:83], v[180:183], v[206:209], v[80:83]
	v_mfma_f32_16x16x32_bf16 v[68:71], v[172:175], v[214:217], v[68:71]
	v_mfma_f32_16x16x32_bf16 v[64:67], v[180:183], v[214:217], v[64:67]
	s_barrier
	s_add_i32 s59, s53, s39
	v_lshl_add_u64 v[168:169], s[34:35], 0, v[128:129]
	s_mov_b32 m0, s59
	ds_read_b128 v[184:187], v146 offset:16384
	ds_read_b128 v[188:191], v146 offset:17408
	ds_read_b128 v[192:195], v146 offset:18432
	ds_read_b128 v[196:199], v146 offset:19456
	ds_read_b128 v[202:205], v146 offset:20480
	ds_read_b128 v[206:209], v146 offset:21504
	ds_read_b128 v[210:213], v146 offset:22528
	ds_read_b128 v[214:217], v146 offset:23552
	global_load_lds_dwordx4 v[168:169], off
	s_add_i32 m0, s59, 0x2000
	s_add_u32 s60, s34, 0x80000
	v_lshl_add_u64 v[218:219], s[34:35], 0, v[130:131]
	s_addc_u32 s61, s35, 0
	s_add_i32 s59, s54, s39
	global_load_lds_dwordx4 v[218:219], off
	v_lshl_add_u64 v[220:221], s[60:61], 0, v[128:129]
	s_mov_b32 m0, s59
	v_lshl_add_u64 v[222:223], s[36:37], 0, v[130:131]
	global_load_lds_dwordx4 v[220:221], off
	v_lshl_add_u64 v[220:221], s[60:61], 0, v[130:131]
	s_add_i32 m0, s59, 0x2000
	s_nop 0
	global_load_lds_dwordx4 v[220:221], off
	v_lshl_add_u64 v[220:221], s[36:37], 0, v[128:129]
	s_mov_b32 m0, s40
	s_nop 0
	global_load_lds_dwordx4 v[220:221], off
	s_mov_b32 m0, s41
	s_nop 0
	global_load_lds_dwordx4 v[222:223], off
	s_waitcnt vmcnt(8)
	s_waitcnt lgkmcnt(0)
	s_barrier
	s_waitcnt lgkmcnt(0)
	v_mfma_f32_16x16x32_bf16 v[60:63], v[148:151], v[184:187], v[60:63]
	v_mfma_f32_16x16x32_bf16 v[56:59], v[156:159], v[184:187], v[56:59]
	v_mfma_f32_16x16x32_bf16 v[44:47], v[148:151], v[192:195], v[44:47]
	v_mfma_f32_16x16x32_bf16 v[40:43], v[156:159], v[192:195], v[40:43]
	v_mfma_f32_16x16x32_bf16 v[28:31], v[148:151], v[202:205], v[28:31]
	v_mfma_f32_16x16x32_bf16 v[24:27], v[156:159], v[202:205], v[24:27]
	v_mfma_f32_16x16x32_bf16 v[12:15], v[148:151], v[210:213], v[12:15]
	v_mfma_f32_16x16x32_bf16 v[8:11], v[156:159], v[210:213], v[8:11]
	v_mfma_f32_16x16x32_bf16 v[60:63], v[152:155], v[188:191], v[60:63]
	v_mfma_f32_16x16x32_bf16 v[56:59], v[160:163], v[188:191], v[56:59]
	v_mfma_f32_16x16x32_bf16 v[44:47], v[152:155], v[196:199], v[44:47]
	v_mfma_f32_16x16x32_bf16 v[40:43], v[160:163], v[196:199], v[40:43]
	v_mfma_f32_16x16x32_bf16 v[28:31], v[152:155], v[206:209], v[28:31]
	v_mfma_f32_16x16x32_bf16 v[24:27], v[160:163], v[206:209], v[24:27]
	v_mfma_f32_16x16x32_bf16 v[12:15], v[152:155], v[214:217], v[12:15]
	v_mfma_f32_16x16x32_bf16 v[8:11], v[160:163], v[214:217], v[8:11]
	v_mfma_f32_16x16x32_bf16 v[52:55], v[164:167], v[184:187], v[52:55]
	v_mfma_f32_16x16x32_bf16 v[48:51], v[176:179], v[184:187], v[48:51]
	v_mfma_f32_16x16x32_bf16 v[36:39], v[164:167], v[192:195], v[36:39]
	v_mfma_f32_16x16x32_bf16 v[32:35], v[176:179], v[192:195], v[32:35]
	v_mfma_f32_16x16x32_bf16 v[20:23], v[164:167], v[202:205], v[20:23]
	v_mfma_f32_16x16x32_bf16 v[16:19], v[176:179], v[202:205], v[16:19]
	v_mfma_f32_16x16x32_bf16 v[4:7], v[164:167], v[210:213], v[4:7]
	v_mfma_f32_16x16x32_bf16 v[0:3], v[176:179], v[210:213], v[0:3]
	v_mfma_f32_16x16x32_bf16 v[52:55], v[172:175], v[188:191], v[52:55]
	v_mfma_f32_16x16x32_bf16 v[48:51], v[180:183], v[188:191], v[48:51]
	v_mfma_f32_16x16x32_bf16 v[36:39], v[172:175], v[196:199], v[36:39]
	v_mfma_f32_16x16x32_bf16 v[32:35], v[180:183], v[196:199], v[32:35]
	v_mfma_f32_16x16x32_bf16 v[20:23], v[172:175], v[206:209], v[20:23]
	v_mfma_f32_16x16x32_bf16 v[16:19], v[180:183], v[206:209], v[16:19]
	v_mfma_f32_16x16x32_bf16 v[4:7], v[172:175], v[214:217], v[4:7]
	v_mfma_f32_16x16x32_bf16 v[0:3], v[180:183], v[214:217], v[0:3]
	s_barrier
	s_add_i32 s59, 0, 0x18000
	v_add_u32_e32 v147, s59, v145
	s_add_i32 s60, 0, 0x1c000
	ds_read_b128 v[148:151], v147
	ds_read_b128 v[152:155], v147 offset:1024
	ds_read_b128 v[156:159], v147 offset:2048
	ds_read_b128 v[160:163], v147 offset:3072
	v_add_u32_e32 v147, s60, v145
	ds_read_b128 v[164:167], v147
	ds_read_b128 v[172:175], v147 offset:1024
	ds_read_b128 v[176:179], v147 offset:2048
	ds_read_b128 v[180:183], v147 offset:3072
	s_add_u32 s36, s36, 0x80000
	s_addc_u32 s37, s37, 0
	s_mov_b32 m0, s43
	v_lshl_add_u64 v[224:225], s[36:37], 0, v[128:129]
	ds_read_b128 v[184:187], v146 offset:32768
	ds_read_b128 v[188:191], v146 offset:33792
	ds_read_b128 v[192:195], v146 offset:34816
	ds_read_b128 v[196:199], v146 offset:35840
	ds_read_b128 v[202:205], v146 offset:36864
	ds_read_b128 v[206:209], v146 offset:37888
	ds_read_b128 v[210:213], v146 offset:38912
	ds_read_b128 v[214:217], v146 offset:39936
	global_load_lds_dwordx4 v[224:225], off
	v_lshl_add_u64 v[224:225], s[36:37], 0, v[130:131]
	s_mov_b32 m0, s48
	s_nop 0
	global_load_lds_dwordx4 v[224:225], off
	s_waitcnt vmcnt(8)
	s_waitcnt lgkmcnt(0)
	s_barrier
	s_waitcnt lgkmcnt(0)
	v_mfma_f32_16x16x32_bf16 v[124:127], v[148:151], v[184:187], v[124:127]
	v_mfma_f32_16x16x32_bf16 v[120:123], v[156:159], v[184:187], v[120:123]
	v_mfma_f32_16x16x32_bf16 v[108:111], v[148:151], v[192:195], v[108:111]
	v_mfma_f32_16x16x32_bf16 v[104:107], v[156:159], v[192:195], v[104:107]
	v_mfma_f32_16x16x32_bf16 v[92:95], v[148:151], v[202:205], v[92:95]
	v_mfma_f32_16x16x32_bf16 v[88:91], v[156:159], v[202:205], v[88:91]
	v_mfma_f32_16x16x32_bf16 v[76:79], v[148:151], v[210:213], v[76:79]
	v_mfma_f32_16x16x32_bf16 v[72:75], v[156:159], v[210:213], v[72:75]
	v_mfma_f32_16x16x32_bf16 v[124:127], v[152:155], v[188:191], v[124:127]
	v_mfma_f32_16x16x32_bf16 v[120:123], v[160:163], v[188:191], v[120:123]
	v_mfma_f32_16x16x32_bf16 v[108:111], v[152:155], v[196:199], v[108:111]
	v_mfma_f32_16x16x32_bf16 v[104:107], v[160:163], v[196:199], v[104:107]
	v_mfma_f32_16x16x32_bf16 v[92:95], v[152:155], v[206:209], v[92:95]
	v_mfma_f32_16x16x32_bf16 v[88:91], v[160:163], v[206:209], v[88:91]
	v_mfma_f32_16x16x32_bf16 v[76:79], v[152:155], v[214:217], v[76:79]
	v_mfma_f32_16x16x32_bf16 v[72:75], v[160:163], v[214:217], v[72:75]
	v_mfma_f32_16x16x32_bf16 v[116:119], v[164:167], v[184:187], v[116:119]
	v_mfma_f32_16x16x32_bf16 v[112:115], v[176:179], v[184:187], v[112:115]
	v_mfma_f32_16x16x32_bf16 v[100:103], v[164:167], v[192:195], v[100:103]
	v_mfma_f32_16x16x32_bf16 v[96:99], v[176:179], v[192:195], v[96:99]
	v_mfma_f32_16x16x32_bf16 v[84:87], v[164:167], v[202:205], v[84:87]
	v_mfma_f32_16x16x32_bf16 v[80:83], v[176:179], v[202:205], v[80:83]
	v_mfma_f32_16x16x32_bf16 v[68:71], v[164:167], v[210:213], v[68:71]
	v_mfma_f32_16x16x32_bf16 v[64:67], v[176:179], v[210:213], v[64:67]
	v_mfma_f32_16x16x32_bf16 v[116:119], v[172:175], v[188:191], v[116:119]
	v_mfma_f32_16x16x32_bf16 v[112:115], v[180:183], v[188:191], v[112:115]
	v_mfma_f32_16x16x32_bf16 v[100:103], v[172:175], v[196:199], v[100:103]
	v_mfma_f32_16x16x32_bf16 v[96:99], v[180:183], v[196:199], v[96:99]
	v_mfma_f32_16x16x32_bf16 v[84:87], v[172:175], v[206:209], v[84:87]
	v_mfma_f32_16x16x32_bf16 v[80:83], v[180:183], v[206:209], v[80:83]
	v_mfma_f32_16x16x32_bf16 v[68:71], v[172:175], v[214:217], v[68:71]
	v_mfma_f32_16x16x32_bf16 v[64:67], v[180:183], v[214:217], v[64:67]
	s_barrier
	s_add_i32 s36, s59, s39
	v_lshl_add_u64 v[168:169], v[168:169], 0, s[18:19]
	s_mov_b32 m0, s36
	ds_read_b128 v[184:187], v146 offset:49152
	ds_read_b128 v[188:191], v146 offset:50176
	ds_read_b128 v[192:195], v146 offset:51200
	ds_read_b128 v[196:199], v146 offset:52224
	ds_read_b128 v[202:205], v146 offset:53248
	ds_read_b128 v[206:209], v146 offset:54272
	ds_read_b128 v[210:213], v146 offset:55296
	ds_read_b128 v[214:217], v146 offset:56320
	global_load_lds_dwordx4 v[168:169], off
	s_add_i32 m0, s36, 0x2000
	s_add_u32 s34, s34, 0x80080
	v_lshl_add_u64 v[168:169], v[218:219], 0, s[18:19]
	s_addc_u32 s35, s35, 0
	s_add_i32 s36, s60, s39
	global_load_lds_dwordx4 v[168:169], off
	v_lshl_add_u64 v[168:169], s[34:35], 0, v[128:129]
	s_mov_b32 m0, s36
	s_nop 0
	global_load_lds_dwordx4 v[168:169], off
	v_lshl_add_u64 v[168:169], s[34:35], 0, v[130:131]
	s_add_i32 m0, s36, 0x2000
	s_nop 0
	global_load_lds_dwordx4 v[168:169], off
	v_lshl_add_u64 v[168:169], v[220:221], 0, s[18:19]
	s_mov_b32 m0, s49
	s_nop 0
	global_load_lds_dwordx4 v[168:169], off
	v_lshl_add_u64 v[168:169], v[222:223], 0, s[18:19]
	s_mov_b32 m0, s50
	s_nop 0
	global_load_lds_dwordx4 v[168:169], off
	s_waitcnt vmcnt(8)
	s_waitcnt lgkmcnt(0)
	s_barrier
	s_waitcnt lgkmcnt(0)
	v_mfma_f32_16x16x32_bf16 v[60:63], v[148:151], v[184:187], v[60:63]
	v_mfma_f32_16x16x32_bf16 v[56:59], v[156:159], v[184:187], v[56:59]
	v_mfma_f32_16x16x32_bf16 v[44:47], v[148:151], v[192:195], v[44:47]
	v_mfma_f32_16x16x32_bf16 v[40:43], v[156:159], v[192:195], v[40:43]
	v_mfma_f32_16x16x32_bf16 v[28:31], v[148:151], v[202:205], v[28:31]
	v_mfma_f32_16x16x32_bf16 v[24:27], v[156:159], v[202:205], v[24:27]
	v_mfma_f32_16x16x32_bf16 v[12:15], v[148:151], v[210:213], v[12:15]
	v_mfma_f32_16x16x32_bf16 v[8:11], v[156:159], v[210:213], v[8:11]
	v_mfma_f32_16x16x32_bf16 v[60:63], v[152:155], v[188:191], v[60:63]
	v_mfma_f32_16x16x32_bf16 v[56:59], v[160:163], v[188:191], v[56:59]
	v_mfma_f32_16x16x32_bf16 v[44:47], v[152:155], v[196:199], v[44:47]
	v_mfma_f32_16x16x32_bf16 v[40:43], v[160:163], v[196:199], v[40:43]
	v_mfma_f32_16x16x32_bf16 v[28:31], v[152:155], v[206:209], v[28:31]
	v_mfma_f32_16x16x32_bf16 v[24:27], v[160:163], v[206:209], v[24:27]
	v_mfma_f32_16x16x32_bf16 v[12:15], v[152:155], v[214:217], v[12:15]
	v_mfma_f32_16x16x32_bf16 v[8:11], v[160:163], v[214:217], v[8:11]
	v_mfma_f32_16x16x32_bf16 v[52:55], v[164:167], v[184:187], v[52:55]
	v_mfma_f32_16x16x32_bf16 v[48:51], v[176:179], v[184:187], v[48:51]
	v_mfma_f32_16x16x32_bf16 v[36:39], v[164:167], v[192:195], v[36:39]
	v_mfma_f32_16x16x32_bf16 v[32:35], v[176:179], v[192:195], v[32:35]
	v_mfma_f32_16x16x32_bf16 v[20:23], v[164:167], v[202:205], v[20:23]
	v_mfma_f32_16x16x32_bf16 v[16:19], v[176:179], v[202:205], v[16:19]
	v_mfma_f32_16x16x32_bf16 v[4:7], v[164:167], v[210:213], v[4:7]
	v_mfma_f32_16x16x32_bf16 v[0:3], v[176:179], v[210:213], v[0:3]
	v_mfma_f32_16x16x32_bf16 v[52:55], v[172:175], v[188:191], v[52:55]
	v_mfma_f32_16x16x32_bf16 v[48:51], v[180:183], v[188:191], v[48:51]
	v_mfma_f32_16x16x32_bf16 v[36:39], v[172:175], v[196:199], v[36:39]
	v_mfma_f32_16x16x32_bf16 v[32:35], v[180:183], v[196:199], v[32:35]
	v_mfma_f32_16x16x32_bf16 v[20:23], v[172:175], v[206:209], v[20:23]
	v_mfma_f32_16x16x32_bf16 v[16:19], v[180:183], v[206:209], v[16:19]
	v_mfma_f32_16x16x32_bf16 v[4:7], v[172:175], v[214:217], v[4:7]
	v_mfma_f32_16x16x32_bf16 v[0:3], v[180:183], v[214:217], v[0:3]
	s_barrier
	s_add_i32 s58, s58, 2
	s_add_u32 s30, s30, 0x100
	s_addc_u32 s31, s31, 0
	s_cmp_gt_u32 s58, 29
	s_cbranch_scc0 .LBB0_495
	s_setprio 0
	s_add_u32 s30, s27, 0xffffff00
	s_addc_u32 s31, s55, -1
	s_andn2_b64 vcc, exec, s[4:5]
	s_cbranch_vccnz .LBB0_498
	v_mov_b32_e32 v0, 0
	s_mov_b32 s51, s20
	s_mov_b32 s14, s22
	s_mov_b64 s[16:17], s[28:29]
	s_mov_b32 s52, s26
	v_mov_b32_e32 v1, v0
	v_mov_b32_e32 v2, v0
	v_mov_b32_e32 v3, v0
	v_mov_b32_e32 v4, v0
	v_mov_b32_e32 v5, v0
	v_mov_b32_e32 v6, v0
	v_mov_b32_e32 v7, v0
	v_mov_b32_e32 v16, v0
	v_mov_b32_e32 v17, v0
	v_mov_b32_e32 v18, v0
	v_mov_b32_e32 v19, v0
	v_mov_b32_e32 v20, v0
	v_mov_b32_e32 v21, v0
	v_mov_b32_e32 v22, v0
	v_mov_b32_e32 v23, v0
	v_mov_b32_e32 v32, v0
	v_mov_b32_e32 v33, v0
	v_mov_b32_e32 v34, v0
	v_mov_b32_e32 v35, v0
	v_mov_b32_e32 v36, v0
	v_mov_b32_e32 v37, v0
	v_mov_b32_e32 v38, v0
	v_mov_b32_e32 v39, v0
	v_mov_b32_e32 v48, v0
	v_mov_b32_e32 v49, v0
	v_mov_b32_e32 v50, v0
	v_mov_b32_e32 v51, v0
	v_mov_b32_e32 v52, v0
	v_mov_b32_e32 v53, v0
	v_mov_b32_e32 v54, v0
	v_mov_b32_e32 v55, v0
	v_mov_b32_e32 v8, v0
	v_mov_b32_e32 v9, v0
	v_mov_b32_e32 v10, v0
	v_mov_b32_e32 v11, v0
	v_mov_b32_e32 v12, v0
	v_mov_b32_e32 v13, v0
	v_mov_b32_e32 v14, v0
	v_mov_b32_e32 v15, v0
	v_mov_b32_e32 v24, v0
	v_mov_b32_e32 v25, v0
	v_mov_b32_e32 v26, v0
	v_mov_b32_e32 v27, v0
	v_mov_b32_e32 v28, v0
	v_mov_b32_e32 v29, v0
	v_mov_b32_e32 v30, v0
	v_mov_b32_e32 v31, v0
	v_mov_b32_e32 v40, v0
	v_mov_b32_e32 v41, v0
	v_mov_b32_e32 v42, v0
	v_mov_b32_e32 v43, v0
	v_mov_b32_e32 v44, v0
	v_mov_b32_e32 v45, v0
	v_mov_b32_e32 v46, v0
	v_mov_b32_e32 v47, v0
	v_mov_b32_e32 v56, v0
	v_mov_b32_e32 v57, v0
	v_mov_b32_e32 v58, v0
	v_mov_b32_e32 v59, v0
	v_mov_b32_e32 v60, v0
	v_mov_b32_e32 v61, v0
	v_mov_b32_e32 v62, v0
	v_mov_b32_e32 v63, v0
	v_mov_b32_e32 v64, v0
	v_mov_b32_e32 v65, v0
	v_mov_b32_e32 v66, v0
	v_mov_b32_e32 v67, v0
	v_mov_b32_e32 v68, v0
	v_mov_b32_e32 v69, v0
	v_mov_b32_e32 v70, v0
	v_mov_b32_e32 v71, v0
	v_mov_b32_e32 v80, v0
	v_mov_b32_e32 v81, v0
	v_mov_b32_e32 v82, v0
	v_mov_b32_e32 v83, v0
	v_mov_b32_e32 v84, v0
	v_mov_b32_e32 v85, v0
	v_mov_b32_e32 v86, v0
	v_mov_b32_e32 v87, v0
	v_mov_b32_e32 v96, v0
	v_mov_b32_e32 v97, v0
	v_mov_b32_e32 v98, v0
	v_mov_b32_e32 v99, v0
	v_mov_b32_e32 v100, v0
	v_mov_b32_e32 v101, v0
	v_mov_b32_e32 v102, v0
	v_mov_b32_e32 v103, v0
	v_mov_b32_e32 v112, v0
	v_mov_b32_e32 v113, v0
	v_mov_b32_e32 v114, v0
	v_mov_b32_e32 v115, v0
	v_mov_b32_e32 v116, v0
	v_mov_b32_e32 v117, v0
	v_mov_b32_e32 v118, v0
	v_mov_b32_e32 v119, v0
	v_mov_b32_e32 v72, v0
	v_mov_b32_e32 v73, v0
	v_mov_b32_e32 v74, v0
	v_mov_b32_e32 v75, v0
	v_mov_b32_e32 v76, v0
	v_mov_b32_e32 v77, v0
	v_mov_b32_e32 v78, v0
	v_mov_b32_e32 v79, v0
	v_mov_b32_e32 v88, v0
	v_mov_b32_e32 v89, v0
	v_mov_b32_e32 v90, v0
	v_mov_b32_e32 v91, v0
	v_mov_b32_e32 v92, v0
	v_mov_b32_e32 v93, v0
	v_mov_b32_e32 v94, v0
	v_mov_b32_e32 v95, v0
	v_mov_b32_e32 v104, v0
	v_mov_b32_e32 v105, v0
	v_mov_b32_e32 v106, v0
	v_mov_b32_e32 v107, v0
	v_mov_b32_e32 v108, v0
	v_mov_b32_e32 v109, v0
	v_mov_b32_e32 v110, v0
	v_mov_b32_e32 v111, v0
	v_mov_b32_e32 v120, v0
	v_mov_b32_e32 v121, v0
	v_mov_b32_e32 v122, v0
	v_mov_b32_e32 v123, v0
	v_mov_b32_e32 v124, v0
	v_mov_b32_e32 v125, v0
	v_mov_b32_e32 v126, v0
	v_mov_b32_e32 v127, v0
	s_andn2_b64 vcc, exec, s[0:1]
	s_cbranch_vccnz .LBB0_499
	s_branch .LBB0_500
